# v3 + nt hint on the final-norm phase's f32 output stores (never re-read by the kernel)
# speedup vs baseline: 1.0189x; 1.0019x over previous
.LBB0_1860:
	v_ashrrev_i32_e32 v1, 31, v0
	v_lshl_add_u64 v[16:17], v[0:1], 2, s[0:1]
	global_load_dword v15, v[16:17], off
	v_lshlrev_b64 v[16:17], 11, v[0:1]
	v_lshl_add_u64 v[28:29], s[34:35], 0, v[16:17]
	v_lshl_add_u64 v[30:31], v[28:29], 0, v[2:3]
	global_load_dwordx4 v[16:19], v[30:31], off
	global_load_dwordx4 v[20:23], v[4:5], off
	global_load_dwordx4 v[24:27], v[4:5], off offset:16
	v_lshlrev_b64 v[30:31], 12, v[0:1]
	v_lshl_add_u64 v[30:31], s[50:51], 0, v[30:31]
	v_lshl_add_u64 v[32:33], v[30:31], 0, v[8:9]
	v_lshl_add_u64 v[28:29], v[28:29], 0, v[10:11]
	v_add_u32_e32 v0, s4, v0
	s_waitcnt vmcnt(3)
	v_fmamk_f32 v1, v15, 0x3a800000, v14
	v_mul_f32_e32 v15, 0x4b800000, v1
	v_cmp_gt_f32_e32 vcc, s5, v1
	s_waitcnt vmcnt(2)
	v_lshlrev_b32_e32 v34, 16, v16
	v_and_b32_e32 v35, 0xffff0000, v16
	v_cndmask_b32_e32 v1, v1, v15, vcc
	v_rsq_f32_e32 v1, v1
	v_lshlrev_b32_e32 v16, 16, v17
	v_and_b32_e32 v17, 0xffff0000, v17
	v_lshlrev_b32_e32 v36, 16, v18
	v_mul_f32_e32 v15, 0x45800000, v1
	v_cndmask_b32_e32 v38, v1, v15, vcc
	v_and_b32_e32 v37, 0xffff0000, v18
	v_lshlrev_b32_e32 v18, 16, v19
	v_and_b32_e32 v19, 0xffff0000, v19
	v_pk_mul_f32 v[34:35], v[38:39], v[34:35] op_sel_hi:[0,1]
	v_pk_mul_f32 v[16:17], v[38:39], v[16:17] op_sel_hi:[0,1]
	v_pk_mul_f32 v[36:37], v[38:39], v[36:37] op_sel_hi:[0,1]
	v_pk_mul_f32 v[40:41], v[38:39], v[18:19] op_sel_hi:[0,1]
	s_waitcnt vmcnt(1)
	v_pk_mul_f32 v[18:19], v[22:23], v[16:17]
	v_pk_mul_f32 v[16:17], v[20:21], v[34:35]
	s_waitcnt vmcnt(0)
	v_pk_mul_f32 v[22:23], v[26:27], v[40:41]
	v_pk_mul_f32 v[20:21], v[24:25], v[36:37]
	global_store_dwordx4 v[32:33], v[16:19], off nt
	global_store_dwordx4 v[32:33], v[20:23], off offset:16 nt
	global_load_dwordx4 v[16:19], v[28:29], off
	s_nop 0
	global_load_dwordx4 v[20:23], v[6:7], off
	global_load_dwordx4 v[24:27], v[6:7], off offset:16
	v_lshl_add_u64 v[28:29], v[30:31], 0, v[12:13]
	v_cmp_lt_i32_e32 vcc, s6, v0
	s_or_b64 s[2:3], vcc, s[2:3]
	s_waitcnt vmcnt(2)
	v_lshlrev_b32_e32 v30, 16, v16
	v_and_b32_e32 v31, 0xffff0000, v16
	v_lshlrev_b32_e32 v16, 16, v17
	v_and_b32_e32 v17, 0xffff0000, v17
	v_lshlrev_b32_e32 v32, 16, v18
	v_and_b32_e32 v33, 0xffff0000, v18
	v_lshlrev_b32_e32 v18, 16, v19
	v_and_b32_e32 v19, 0xffff0000, v19
	v_pk_mul_f32 v[30:31], v[38:39], v[30:31] op_sel_hi:[0,1]
	v_pk_mul_f32 v[16:17], v[38:39], v[16:17] op_sel_hi:[0,1]
	v_pk_mul_f32 v[32:33], v[38:39], v[32:33] op_sel_hi:[0,1]
	v_pk_mul_f32 v[34:35], v[38:39], v[18:19] op_sel_hi:[0,1]
	s_waitcnt vmcnt(1)
	v_pk_mul_f32 v[18:19], v[22:23], v[16:17]
	v_pk_mul_f32 v[16:17], v[20:21], v[30:31]
	s_waitcnt vmcnt(0)
	v_pk_mul_f32 v[22:23], v[26:27], v[34:35]
	v_pk_mul_f32 v[20:21], v[24:25], v[32:33]
	global_store_dwordx4 v[28:29], v[16:19], off nt
	global_store_dwordx4 v[28:29], v[20:23], off offset:16 nt
	s_andn2_b64 exec, exec, s[2:3]
	s_cbranch_execnz .LBB0_1860
